# idle chain-phase workgroups convert the next layer's W_in (moved out of the LN phase)
# baseline (speedup 1.0000x reference)
.LBB0_104:
	s_or_b64 exec, exec, s[16:17]
	s_and_b64 vcc, exec, s[40:41]
	v_readlane_b32 s11, v254, 54
	s_mov_b32 s10, 0x3d800000
	s_mov_b32 s13, s25
	s_mov_b32 s16, s35
	s_cbranch_vccz .LBB0_144
	s_and_b64 s[0:1], s[38:39], exec
	s_movk_i32 s0, 0x410
	s_cselect_b32 s4, s0, 0x500
	s_cselect_b32 s100, 0, 0x400
	s_mov_b32 s101, 0
	s_add_i32 s0, s20, s100
	s_cmp_ge_i32 s0, s4
	s_cbranch_scc1 .LBB0_144
.Lconv_entry:
	v_readlane_b32 s0, v254, 55
	s_add_i32 s0, s0, 1
	s_ashr_i32 s6, s0, 1
	s_ashr_i32 s7, s6, 31
	s_ashr_i32 s1, s0, 31
	s_lshl_b64 s[8:9], s[6:7], 17
	s_lshl_b64 s[10:11], s[0:1], 22
	s_lshl_b64 s[12:13], s[6:7], 24
	s_add_u32 s0, s94, 0xf200000
	s_addc_u32 s1, s95, 0
	s_add_u32 s5, s94, 0xfa00000
	v_readlane_b32 s40, v253, 20
	s_mul_hi_i32 s14, s6, 0xc00000
	s_mul_i32 s15, s6, 0xc00000
	s_addc_u32 s6, s95, 0
	v_readlane_b32 s52, v253, 32
	v_readlane_b32 s53, v253, 33
	s_add_u32 s12, s52, s12
	s_addc_u32 s13, s53, s13
	v_readlane_b32 s41, v253, 21
	s_add_u32 s10, s40, s10
	v_readlane_b32 s44, v253, 24
	s_addc_u32 s11, s41, s11
	v_readlane_b32 s45, v253, 25
	s_add_u32 s28, s44, s8
	v_readlane_b32 s42, v253, 22
	s_addc_u32 s29, s45, s9
	v_readlane_b32 s43, v253, 23
	v_lshlrev_b32_e32 v0, 2, v133
	s_add_u32 s8, s42, s15
	s_waitcnt vmcnt(0)
	v_and_b32_e32 v2, 0xf0, v0
	v_mov_b32_e32 v3, v1
	s_addc_u32 s9, s43, s14
	v_lshl_add_u64 v[4:5], s[12:13], 0, v[2:3]
	v_lshlrev_b32_e32 v0, 3, v134
	v_lshl_add_u64 v[6:7], s[10:11], 0, v[2:3]
	v_lshl_add_u64 v[8:9], s[8:9], 0, v[2:3]
	v_ashrrev_i32_e32 v3, 3, v134
	v_add_u32_e32 v10, 0x100, v134
	s_movk_i32 s7, 0x104
	v_and_b32_e32 v0, 56, v0
	v_ashrrev_i32_e32 v35, 3, v10
	v_lshlrev_b32_e32 v10, 2, v3
	v_mad_u32_u24 v36, v0, s7, v10
	v_lshlrev_b32_e32 v10, 2, v35
	v_mad_u32_u24 v37, v0, s7, v10
	v_max_i32_e32 v10, 0x1f00, v134
	v_sub_u32_e32 v10, v10, v134
	v_add_u32_e32 v10, 0xff, v10
	v_ashrrev_i32_e32 v30, 4, v134
	v_lshrrev_b32_e32 v11, 8, v10
	v_mul_lo_u32 v31, v30, s7
	v_add_u32_e32 v11, 1, v11
	v_and_b32_e32 v12, 0x300, v10
	s_movk_i32 s7, 0x300
	v_and_b32_e32 v11, 3, v11
	v_cmp_ne_u32_e64 s[40:41], s7, v12
	s_movk_i32 s7, 0x2ff
	v_add_u32_e32 v32, 16, v30
	v_add_u32_e32 v33, 32, v30
	v_add_u32_e32 v34, 48, v30
	v_cmp_gt_i32_e64 s[38:39], s37, v134
	v_cmp_lt_u32_e64 s[42:43], s7, v10
	v_sub_u32_e32 v38, 0, v11
	v_lshlrev_b32_e32 v10, 1, v0
	s_add_i32 s7, s20, s100
	v_readlane_b32 s46, v253, 26
	v_readlane_b32 s47, v253, 27
	v_readlane_b32 s48, v253, 28
	v_readlane_b32 s49, v253, 29
	v_readlane_b32 s50, v253, 30
	v_readlane_b32 s51, v253, 31
	v_readlane_b32 s54, v253, 34
	v_readlane_b32 s55, v253, 35
	s_branch .LBB0_108

.LBB0_143:
	s_cmp_eq_u32 s101, 1
	s_cbranch_scc0 .Lconv_ret_ln
	s_mov_b64 s[0:1], 0
	s_branch .LBB0_171

.Lchain_idle_conv:
	s_sub_i32 s20, s20, 0x100
	s_movk_i32 s34, 0x100
	s_movk_i32 s4, 0x400
	s_mov_b32 s100, 0
	s_mov_b32 s101, 1
	v_lshlrev_b32_e32 v133, 2, v134
	s_branch .Lconv_entry
